# in-phase counter waits (attention entry, full-unit group wait, deferred fix-up wait, out-proj row-stat exchange): acquire invalidate issued with the first counter poll instead of after it
# speedup vs baseline: 1.0074x; 1.0004x over previous
; #define LAS __attribute__((address_space(3)))
; __device__ __forceinline__ unsigned xb_ld(unsigned* p)              { return __hip_atomic_load(p, __ATOMIC_RELAXED, __HIP_MEMORY_SCOPE_AGENT); }
; __device__ __forceinline__ void group_wait(unsigned* cnt, unsigned want, unsigned* bar) {
;     if (threadIdx.x == 0) {
;         unsigned sp = 0;
;         while (__hip_atomic_load(cnt, __ATOMIC_RELAXED, __HIP_MEMORY_SCOPE_AGENT) < want) {
;             __builtin_amdgcn_s_sleep(2);
;             if ((++sp & 255u) == 0u) { if (xb_ld(&bar[XB_TMO])) break; if (sp > XB_SPIN_CAP) { atomicAdd(&bar[XB_TMO], 1u); break; } }
;         }
;         __builtin_amdgcn_fence(__ATOMIC_ACQUIRE, "agent");
;         asm volatile("s_waitcnt vmcnt(0)" ::: "memory");
;     }
; __global__ void __launch_bounds__(NWAVES * 64, 2) fwd_megakernel(Args a) {
;     ...
;             const int gb = blockIdx.x & 7, l = blockIdx.x >> 3;
;             if (l >= 8) {
;                 group_wait(gca, 256u, (unsigned*)(ws + WS_BAR));
;                 attn_unit(lds, gb * 32 + l, 0, QKVG, a.sinks, a.norm_attn, MIX, SSA);
;                 {
;                     LAS float* scr = (LAS float*)(lds + wave * 16384);
;                     constexpr int I_OUT = (DMIX / 64) * (DM / 32);
;                     const int it = ((blockIdx.x & 7) * 24 + (l - 8)) * NWAVES + wave;
;                     if (it < I_OUT) p0_transpose_item<false>(a.w_out, DMIX, DM, WOUT, scr, it, lane);
;                     __syncthreads();
;                 }
;             } else group_wait(gca, 256u, (unsigned*)(ws + WS_BAR));
.LBB0_257:
	s_or_b64 exec, exec, s[0:1]
	s_cmp_lt_u32 s98, 64
	s_cbranch_scc0 .LBB0_268
	s_mov_b64 s[0:1], exec
	v_readlane_b32 s2, v253, 23
	v_readlane_b32 s3, v253, 24
	s_and_b64 s[2:3], s[0:1], s[2:3]
	s_mov_b64 exec, s[2:3]
	s_cbranch_execz .LBB0_274
	v_readlane_b32 s2, v253, 37
	v_mov_b32_e32 v0, 0
	v_readlane_b32 s3, v253, 38
	s_movk_i32 s12, 0xff
	s_nop 3
	buffer_inv sc1
	global_load_dword v1, v0, s[2:3] sc1
	s_waitcnt vmcnt(0)
	v_cmp_lt_u32_e32 vcc, s12, v1
	s_cbranch_vccnz .LBB0_273
	s_add_u32 s2, s96, 0x180200
	s_addc_u32 s3, s97, 0
	s_mov_b32 s13, 1
	s_branch .LBB0_262

; __device__ __forceinline__ void group_wait(unsigned* cnt, unsigned want, unsigned* bar) {
;     ...
;         __builtin_amdgcn_fence(__ATOMIC_ACQUIRE, "agent");
;         asm volatile("s_waitcnt vmcnt(0)" ::: "memory");
.LBB0_273:
	s_waitcnt vmcnt(0)
	s_waitcnt vmcnt(0)

; __device__ __forceinline__ unsigned xb_ld(unsigned* p)              { return __hip_atomic_load(p, __ATOMIC_RELAXED, __HIP_MEMORY_SCOPE_AGENT); }
; __device__ __forceinline__ void group_wait(unsigned* cnt, unsigned want, unsigned* bar) {
;     if (threadIdx.x == 0) {
;         unsigned sp = 0;
;         while (__hip_atomic_load(cnt, __ATOMIC_RELAXED, __HIP_MEMORY_SCOPE_AGENT) < want) {
;             __builtin_amdgcn_s_sleep(2);
;             if ((++sp & 255u) == 0u) { if (xb_ld(&bar[XB_TMO])) break; if (sp > XB_SPIN_CAP) { atomicAdd(&bar[XB_TMO], 1u); break; } }
;         }
;         __builtin_amdgcn_fence(__ATOMIC_ACQUIRE, "agent");
;         asm volatile("s_waitcnt vmcnt(0)" ::: "memory");
;     }
; __global__ void __launch_bounds__(NWAVES * 64, 2) fwd_megakernel(Args a) {
;     ...
;             if (l >= 8) {
;                 group_wait(gca, 256u, (unsigned*)(ws + WS_BAR));
.LBB0_275:
	s_mov_b64 s[0:1], exec
	v_readlane_b32 s2, v253, 23
	v_readlane_b32 s3, v253, 24
	s_and_b64 s[2:3], s[0:1], s[2:3]
	s_mov_b64 exec, s[2:3]
	s_cbranch_execz .LBB0_290
	v_readlane_b32 s2, v253, 37
	v_mov_b32_e32 v0, 0
	v_readlane_b32 s3, v253, 38
	s_movk_i32 s12, 0xff
	s_nop 3
	buffer_inv sc1
	global_load_dword v1, v0, s[2:3] sc1
	s_waitcnt vmcnt(0)
	v_cmp_lt_u32_e32 vcc, s12, v1
	s_cbranch_vccnz .LBB0_289
	s_add_u32 s2, s96, 0x180200
	s_addc_u32 s3, s97, 0
	s_mov_b32 s13, 1
	s_branch .LBB0_279

; __device__ __forceinline__ unsigned xb_ld(unsigned* p)              { return __hip_atomic_load(p, __ATOMIC_RELAXED, __HIP_MEMORY_SCOPE_AGENT); }
; __device__ __forceinline__ void group_wait(unsigned* cnt, unsigned want, unsigned* bar) {
;     if (threadIdx.x == 0) {
;         unsigned sp = 0;
;         while (__hip_atomic_load(cnt, __ATOMIC_RELAXED, __HIP_MEMORY_SCOPE_AGENT) < want) {
;             __builtin_amdgcn_s_sleep(2);
;             if ((++sp & 255u) == 0u) { if (xb_ld(&bar[XB_TMO])) break; if (sp > XB_SPIN_CAP) { atomicAdd(&bar[XB_TMO], 1u); break; } }
;         }
;         __builtin_amdgcn_fence(__ATOMIC_ACQUIRE, "agent");
;         asm volatile("s_waitcnt vmcnt(0)" ::: "memory");
;     }
; __global__ void __launch_bounds__(NWAVES * 64, 2) fwd_megakernel(Args a) {
;     ...
;             if (l >= 24) {
;                 group_wait(gcc, 32u, (unsigned*)(ws + WS_BAR));
;                 if (l != 24 && wave < 2) conv_fixup(2 * (gb * 8 + (l - 24)) + wave, lane, DEF, HALO, a.conv_w, a.norm_conv, MIX, SSC);
.LBB0_313:
	s_or_b64 exec, exec, s[0:1]
	s_cmpk_lt_u32 s98, 0xc0
	s_barrier
	s_cbranch_scc1 .LBB0_339
	s_mov_b64 s[0:1], exec
	v_readlane_b32 s2, v253, 23
	v_readlane_b32 s3, v253, 24
	s_and_b64 s[2:3], s[0:1], s[2:3]
	s_mov_b64 exec, s[2:3]
	s_cbranch_execz .LBB0_329
	v_mov_b32_e32 v0, 0x20448
	ds_read_b32 v1, v0
	s_waitcnt lgkmcnt(0)
	v_cmp_ne_u32_e32 vcc, 0, v1
	s_cbranch_vccnz .LBB0_329
	v_mov_b32_e32 v0, 0
	buffer_inv sc1
	global_load_dword v1, v0, s[8:9] sc1
	s_waitcnt vmcnt(0)
	v_cmp_lt_u32_e32 vcc, 31, v1
	s_cbranch_vccnz .LBB0_328
	s_add_u32 s2, s96, 0x180200
	s_addc_u32 s3, s97, 0
	s_mov_b32 s12, 1
	s_branch .LBB0_318

; __device__ __forceinline__ unsigned xb_ld(unsigned* p)              { return __hip_atomic_load(p, __ATOMIC_RELAXED, __HIP_MEMORY_SCOPE_AGENT); }
;     __device__ __forceinline__ void fused(f32x4 (&acc)[2][2][4][2], const Unit& u, int wr, int wc, int fr, int fq, PG8_LAS unsigned char* lds, int wid, int lane) const {
;     ...
;         asm volatile("s_waitcnt vmcnt(0)" ::: "memory");
;         __syncthreads();
;         if (threadIdx.x == 0) {
;             unsigned* pc = pcnt + 64 * u.pm;
;             __hip_atomic_fetch_add(pc, 1u, __ATOMIC_RELAXED, __HIP_MEMORY_SCOPE_AGENT);
;             unsigned sp = 0;
;             while (__hip_atomic_load(pc, __ATOMIC_RELAXED, __HIP_MEMORY_SCOPE_AGENT) < 4u) {
;                 __builtin_amdgcn_s_sleep(1);
;                 if ((++sp & 255u) == 0u) { if (xb_ld(tmo)) break; if (sp > XB_SPIN_CAP) { atomicAdd(tmo, 1u); break; } }
;             }
;             __builtin_amdgcn_fence(__ATOMIC_ACQUIRE, "agent");
;             asm volatile("s_waitcnt vmcnt(0)" ::: "memory");
.LBB0_548:
	s_or_b64 exec, exec, s[4:5]
	s_waitcnt vmcnt(0)
	s_waitcnt lgkmcnt(0)
	s_barrier
	s_mov_b64 s[2:3], exec
	v_readlane_b32 s4, v253, 23
	v_readlane_b32 s5, v253, 24
	s_and_b64 s[4:5], s[2:3], s[4:5]
	s_mov_b64 exec, s[4:5]
	s_cbranch_execz .LBB0_563
	s_lshl_b32 s0, s0, 6
	s_ashr_i32 s1, s0, 31
	s_lshl_b64 s[0:1], s[0:1], 2
	s_add_u32 s0, s96, s0
	s_addc_u32 s1, s97, s1
	v_mov_b32_e32 v0, 0x18c000
	v_mov_b32_e32 v1, 1
	global_atomic_add v0, v1, s[0:1]
	buffer_inv sc1
	global_load_dword v0, v0, s[0:1] sc1
	s_add_u32 s4, s0, 0x18c000
	s_addc_u32 s5, s1, 0
	s_waitcnt vmcnt(0)
	v_cmp_lt_u32_e32 vcc, 3, v0
	s_cbranch_vccnz .LBB0_562
	s_add_u32 s0, s96, 0x180200
	s_addc_u32 s1, s97, 0
	s_mov_b32 s17, 1
	v_mov_b32_e32 v0, 0
	s_branch .LBB0_552
